# grid barrier: a waiting workgroup issues its L1 invalidate at arrival (no L1 fills can occur while all its waves are parked), not after the release
# speedup vs baseline: 1.0090x; 1.0090x over previous
; __device__ __forceinline__ unsigned xb_ld(unsigned* p)              { return __hip_atomic_load(p, __ATOMIC_RELAXED, __HIP_MEMORY_SCOPE_AGENT); }
; __device__ __forceinline__ unsigned xb_add(unsigned* p, unsigned v) { return __hip_atomic_fetch_add(p, v, __ATOMIC_RELAXED, __HIP_MEMORY_SCOPE_AGENT); }
; #define XB_SPIN(cond, bar) do { unsigned _sp = 0; while (cond) { __builtin_amdgcn_s_sleep(1); \
;     if ((++_sp & 255u) == 0u) { if (xb_ld(&(bar)[XB_TMO])) break; if (_sp > XB_SPIN_CAP) { atomicAdd(&(bar)[XB_TMO], 1u); break; } } } } while (0)
; __device__ __forceinline__ void xcd_barrier(const XcdBarrier& b) {
;     ...
;         const unsigned old = xb_add(&bar[XB_XSUB(b.x)], 1u);
;         const unsigned gen = old / nloc;
;         if (old + 1u == (gen + 1u) * nloc) {
;             __builtin_amdgcn_fence(__ATOMIC_RELEASE, "agent");
;             asm volatile("s_waitcnt vmcnt(0)" ::: "memory");
;             const unsigned og = xb_add(&bar[XB_TOP], 1u);
;             const unsigned tg = og / nx;
;             if (og + 1u == (tg + 1u) * nx) xb_add(&bar[XB_TOPGEN], 1u);
;             else XB_SPIN(xb_ld(&bar[XB_TOPGEN]) == tg, bar);
;             __builtin_amdgcn_fence(__ATOMIC_ACQUIRE, "agent");
;             xb_add(&bar[XB_XGEN(b.x)], 1u);
;             asm volatile("s_waitcnt vmcnt(0)" ::: "memory");
;         } else {
;             XB_SPIN(xb_ld(&bar[XB_XGEN(b.x)]) == gen, bar);
;             __builtin_amdgcn_fence(__ATOMIC_ACQUIRE, "agent");
;             asm volatile("s_waitcnt vmcnt(0)" ::: "memory");
.LBB0_983:
	s_or_b64 exec, exec, s[6:7]
	v_cvt_f32_u32_e32 v4, v2
	s_waitcnt vmcnt(0)
	v_readfirstlane_b32 s0, v3
	v_sub_u32_e32 v3, 0, v2
	v_rcp_iflag_f32_e32 v4, v4
	v_add_u32_e32 v5, s0, v1
	v_mul_f32_e32 v4, 0x4f7ffffe, v4
	v_cvt_u32_f32_e32 v4, v4
	v_mul_lo_u32 v1, v3, v4
	v_mul_hi_u32 v1, v4, v1
	v_add_u32_e32 v1, v4, v1
	v_mul_hi_u32 v1, v5, v1
	v_mul_lo_u32 v3, v1, v2
	v_sub_u32_e32 v3, v5, v3
	v_add_u32_e32 v4, 1, v1
	v_cmp_ge_u32_e32 vcc, v3, v2
	s_nop 1
	v_cndmask_b32_e32 v1, v1, v4, vcc
	v_sub_u32_e32 v4, v3, v2
	v_cndmask_b32_e32 v3, v3, v4, vcc
	v_add_u32_e32 v4, 1, v1
	v_cmp_ge_u32_e32 vcc, v3, v2
	v_add_u32_e32 v3, 1, v5
	s_nop 0
	v_cndmask_b32_e32 v1, v1, v4, vcc
	v_mul_lo_u32 v4, v2, v1
	v_add_u32_e32 v2, v4, v2
	v_cmp_ne_u32_e32 vcc, v3, v2
	s_and_saveexec_b64 s[0:1], vcc
	s_xor_b64 s[6:7], exec, s[0:1]
	s_cbranch_execz .LBB0_1001
	v_readlane_b32 s0, v254, 0
	v_readlane_b32 s1, v254, 1
	s_waitcnt lgkmcnt(0)
	s_nop 3
	buffer_inv sc1
	global_load_dword v0, v33, s[0:1] sc1
	s_waitcnt vmcnt(0)
	v_cmp_eq_u32_e32 vcc, v0, v1
	s_and_saveexec_b64 s[8:9], vcc
	s_cbranch_execz .LBB0_1000
	s_mov_b32 s0, 1
	s_mov_b64 s[16:17], 0
	s_branch .LBB0_987

; __device__ __forceinline__ unsigned xb_ld(unsigned* p)              { return __hip_atomic_load(p, __ATOMIC_RELAXED, __HIP_MEMORY_SCOPE_AGENT); }
; #define XB_SPIN(cond, bar) do { unsigned _sp = 0; while (cond) { __builtin_amdgcn_s_sleep(1); \
;     if ((++_sp & 255u) == 0u) { if (xb_ld(&(bar)[XB_TMO])) break; if (_sp > XB_SPIN_CAP) { atomicAdd(&(bar)[XB_TMO], 1u); break; } } } } while (0)
; __device__ __forceinline__ void xcd_barrier(const XcdBarrier& b) {
;     ...
;             XB_SPIN(xb_ld(&bar[XB_XGEN(b.x)]) == gen, bar);
;             __builtin_amdgcn_fence(__ATOMIC_ACQUIRE, "agent");
;             asm volatile("s_waitcnt vmcnt(0)" ::: "memory");
.LBB0_1000:
	s_or_b64 exec, exec, s[8:9]
	s_waitcnt vmcnt(0)
	s_waitcnt vmcnt(0)
